# v10: v8 + hand-written MLPOUT epilogue (EpiF0) with 3 row-steps of residual loads in flight, waits no longer cover previous step's stores
# speedup vs baseline: 1.0075x; 1.0075x over previous
;     __device__ __forceinline__ void operator()(const typename AccT<I8>::type (&acc)[2][2][4][2], const Unit& u, int wr, int wc, int fr, int fq) const {
;         const int row0 = u.pm * BM + wr * 64 + fr, col0 = u.pn * BM + wc * 32 + 4 * fq;
;         f32x4 sv[2][2];
;         if (I8) {
; #pragma unroll
;             for (int bj = 0; bj < 2; ++bj)
; #pragma unroll
;                 for (int n = 0; n < 2; ++n) sv[bj][n] = *(const f32x4*)(swc + col0 + bj * HALF + n * 16);
;         }
;         float rsv[8];
; #pragma unroll
;         for (int s = 0; s < 8; ++s) { const int r = row0 + (s >> 2) * HALF + (s & 3) * 16; float rs = 1.f; if (MODE == 1) rs = __builtin_amdgcn_rsqf(rstd[r] * (1.0f / 4096.0f) + 1e-6f); if (I8) rs *= sxr[r]; rsv[s] = rs; }
;         RowIn cur, nxt;
;         load_row(cur, (size_t)row0 * 4096 + col0);
; #pragma unroll
;         for (int s = 0; s < 8; ++s) { const int ai = s >> 2, m = s & 3; const int r = row0 + ai * HALF + m * 16; const size_t off = (size_t)r * 4096 + col0;
;                 if (s + 1 < 8) load_row(nxt, (size_t)(row0 + ((s + 1) >> 2) * HALF + ((s + 1) & 3) * 16) * 4096 + col0);
;                 const float rs = rsv[s];
;                 float ss = 0.f, mx = 0.f;
; #pragma unroll
;                 for (int bj = 0; bj < 2; ++bj)
; #pragma unroll
;                     for (int n = 0; n < 2; ++n) { const size_t o = off + bj * HALF + n * 16; const f32x4 b = cur.b[bj][n]; f32x4 v;
;                         if constexpr (I8) v = __builtin_convertvector(acc[ai][bj][m][n], f32x4) * rs * sv[bj][n]; else v = acc[ai][bj][m][n];
;                         if (MODE == 1) { const u32x2 pw = cur.pw[bj][n]; const f32x4 pp = (f32x4){bf_lo(pw.x), bf_hi(pw.x), bf_lo(pw.y), bf_hi(pw.y)}; v = sig4(I8 ? v : v * rs) * pp; }
;                         const f32x4 x = b + v; *(f32x4*)(out + o) = x;
;                         if (MODE == 0 && XB) { u32x2 w; w.x = cvt_pk_bf16(x[0], x[1]); w.y = cvt_pk_bf16(x[2], x[3]); *(u32x2*)(XB + o) = w; ss += (x[0] * x[0] + x[1] * x[1]) + (x[2] * x[2] + x[3] * x[3]);
;                             if (RM) mx = fmaxf(fmaxf(mx, fmaxf(fabsf(x[0]), fabsf(x[1]))), fmaxf(fabsf(x[2]), fabsf(x[3]))); } }
;                 if (MODE == 0 && XB) { ss += __shfl_xor(ss, 16); ss += __shfl_xor(ss, 32); if (fq == 0) unsafeAtomicAdd(SS + r, ss);
.LBB0_2095:
	s_lshl_b32 s98, s6, 4
	s_add_i32 s98, s98, s2
	s_sub_i32 s99, s98, 888
	s_cmp_lt_u32 s98, 888
	s_cselect_b32 s98, s98, s99
	s_mov_b32 s99, 0x4200000
	s_cselect_b32 s99, 0x3f600000, s99
	s_lshl_b32 s98, s98, 18
	s_add_u32 s98, s98, s99
	s_add_u32 s98, s96, s98
	s_addc_u32 s99, s97, 0
	v_and_b32_e32 v244, 63, v0
	v_lshrrev_b32_e32 v245, 6, v0
	v_lshlrev_b32_e32 v246, 4, v244
	v_lshl_add_u32 v246, v245, 15, v246
	v_lshrrev_b32_e32 v245, 8, v0
	v_and_b32_e32 v247, 15, v0
	v_lshl_add_u32 v245, v245, 6, v247
	v_lshl_add_u32 v248, s6, 8, v245
	v_bfe_u32 v245, v0, 6, 2
	v_bfe_u32 v249, v0, 4, 2
	v_lshlrev_b32_e32 v245, 5, v245
	v_lshl_add_u32 v245, v249, 2, v245
	v_lshl_add_u32 v245, s2, 8, v245
	v_lshlrev_b32_e32 v250, 13, v248
	v_lshl_add_u32 v250, v245, 1, v250
	v_lshlrev_b32_e32 v251, 2, v248
	v_xor_b32_e32 v252, 16, v244
	v_xor_b32_e32 v253, 32, v244
	v_lshlrev_b32_e32 v252, 2, v252
	v_lshlrev_b32_e32 v253, 2, v253
	v_cmp_eq_u32_e64 s[6:7], 0, v249
	v_readlane_b32 s52, v254, 40
	v_readlane_b32 s53, v254, 41
	global_load_dwordx4 v[130:133], v246, s[98:99] offset:0
	global_load_dwordx4 v[134:137], v246, s[98:99] offset:1024
	global_load_dwordx4 v[138:141], v246, s[98:99] offset:2048
	global_load_dwordx4 v[142:145], v246, s[98:99] offset:3072
	v_add_u32_e32 v162, 0x1000, v246
	global_load_dwordx4 v[146:149], v162, s[98:99] offset:0
	global_load_dwordx4 v[150:153], v162, s[98:99] offset:1024
	global_load_dwordx4 v[154:157], v162, s[98:99] offset:2048
	global_load_dwordx4 v[158:161], v162, s[98:99] offset:3072
	v_add_u32_e32 v162, 0x2000, v246
	global_load_dwordx4 v[196:199], v162, s[98:99] offset:0
	global_load_dwordx4 v[200:203], v162, s[98:99] offset:1024
	global_load_dwordx4 v[204:207], v162, s[98:99] offset:2048
	global_load_dwordx4 v[208:211], v162, s[98:99] offset:3072
	s_waitcnt vmcnt(8)
	v_pk_add_f32 v[126:127], v[126:127], v[130:131]
	v_pk_add_f32 v[128:129], v[128:129], v[132:133]
	v_pk_add_f32 v[122:123], v[122:123], v[134:135]
	v_pk_add_f32 v[124:125], v[124:125], v[136:137]
	v_pk_add_f32 v[118:119], v[118:119], v[138:139]
	v_pk_add_f32 v[120:121], v[120:121], v[140:141]
	v_pk_add_f32 v[114:115], v[114:115], v[142:143]
	v_pk_add_f32 v[116:117], v[116:117], v[144:145]
	v_add_u32_e32 v162, 0x3000, v246
	global_load_dwordx4 v[130:133], v162, s[98:99] offset:0
	global_load_dwordx4 v[134:137], v162, s[98:99] offset:1024
	global_load_dwordx4 v[138:141], v162, s[98:99] offset:2048
	global_load_dwordx4 v[142:145], v162, s[98:99] offset:3072
	global_store_dwordx4 v246, v[126:129], s[98:99] offset:0
	v_cvt_pk_bf16_f32 v182, v126, v127
	v_cvt_pk_bf16_f32 v183, v128, v129
	v_mul_f32_e32 v166, v127, v127
	v_mul_f32_e32 v167, v129, v129
	global_store_dwordx2 v250, v[182:183], s[52:53] offset:0
	v_fmac_f32_e32 v166, v126, v126
	v_fmac_f32_e32 v167, v128, v128
	v_add_f32_e32 v164, v166, v167
	v_max3_f32 v165, |v126|, |v127|, 0
	v_max3_f32 v165, |v128|, |v129|, v165
	global_store_dwordx4 v246, v[122:125], s[98:99] offset:1024
	v_cvt_pk_bf16_f32 v184, v122, v123
	v_cvt_pk_bf16_f32 v185, v124, v125
	v_mul_f32_e32 v166, v123, v123
	v_mul_f32_e32 v167, v125, v125
	global_store_dwordx2 v250, v[184:185], s[52:53] offset:32
	v_fmac_f32_e32 v166, v122, v122
	v_fmac_f32_e32 v167, v124, v124
	v_add_f32_e32 v166, v166, v167
	v_add_f32_e32 v164, v164, v166
	v_max3_f32 v165, |v122|, |v123|, v165
	v_max3_f32 v165, |v124|, |v125|, v165
	global_store_dwordx4 v246, v[118:121], s[98:99] offset:2048
	v_cvt_pk_bf16_f32 v186, v118, v119
	v_cvt_pk_bf16_f32 v187, v120, v121
	v_mul_f32_e32 v166, v119, v119
	v_mul_f32_e32 v167, v121, v121
	global_store_dwordx2 v250, v[186:187], s[52:53] offset:256
	v_fmac_f32_e32 v166, v118, v118
	v_fmac_f32_e32 v167, v120, v120
	v_add_f32_e32 v166, v166, v167
	v_add_f32_e32 v164, v164, v166
	v_max3_f32 v165, |v118|, |v119|, v165
	v_max3_f32 v165, |v120|, |v121|, v165
	global_store_dwordx4 v246, v[114:117], s[98:99] offset:3072
	v_cvt_pk_bf16_f32 v188, v114, v115
	v_cvt_pk_bf16_f32 v189, v116, v117
	v_mul_f32_e32 v166, v115, v115
	v_mul_f32_e32 v167, v117, v117
	global_store_dwordx2 v250, v[188:189], s[52:53] offset:288
	v_fmac_f32_e32 v166, v114, v114
	v_fmac_f32_e32 v167, v116, v116
	v_add_f32_e32 v166, v166, v167
	v_add_f32_e32 v164, v164, v166
	v_max3_f32 v165, |v114|, |v115|, v165
	v_max3_f32 v165, |v116|, |v117|, v165
	ds_bpermute_b32 v168, v252, v164
	ds_bpermute_b32 v169, v252, v165
	s_waitcnt lgkmcnt(0)
	v_add_f32_e32 v164, v164, v168
	v_max_f32_e32 v165, v165, v169
	ds_bpermute_b32 v168, v253, v164
	ds_bpermute_b32 v169, v253, v165
	s_waitcnt lgkmcnt(0)
	v_add_f32_e32 v164, v164, v168
	v_max_f32_e32 v165, v165, v169
	s_mov_b64 exec, s[6:7]
	global_atomic_add_f32 v251, v164, s[10:11] offset:0
	global_atomic_umax v251, v165, s[12:13] offset:0
	s_mov_b64 exec, -1
	s_waitcnt vmcnt(18)
; __device__ __forceinline__ unsigned cvt_pk_bf16(float lo, float hi) { unsigned r; asm volatile("s_nop 0\n\tv_cvt_pk_bf16_f32 %0, %1, %2" : "=v"(r) : "v"(lo), "v"(hi)); return r; }
; __device__ __forceinline__ f32x4 sig4(const f32x4 v) { return (f32x4){sigmoidf_(v[0]), sigmoidf_(v[1]), sigmoidf_(v[2]), sigmoidf_(v[3])}; }
;     __device__ __forceinline__ void operator()(const typename AccT<I8>::type (&acc)[2][2][4][2], const Unit& u, int wr, int wc, int fr, int fq) const {
;     ...
;         for (int s = 0; s < 8; ++s) { const int ai = s >> 2, m = s & 3; const int r = row0 + ai * HALF + m * 16; const size_t off = (size_t)r * 4096 + col0;
;                 if (s + 1 < 8) load_row(nxt, (size_t)(row0 + ((s + 1) >> 2) * HALF + ((s + 1) & 3) * 16) * 4096 + col0);
;                 const float rs = rsv[s];
;                 float ss = 0.f, mx = 0.f;
; #pragma unroll
;                 for (int bj = 0; bj < 2; ++bj)
; #pragma unroll
;                     for (int n = 0; n < 2; ++n) { const size_t o = off + bj * HALF + n * 16; const f32x4 b = cur.b[bj][n]; f32x4 v;
;                         if constexpr (I8) v = __builtin_convertvector(acc[ai][bj][m][n], f32x4) * rs * sv[bj][n]; else v = acc[ai][bj][m][n];
;                         if (MODE == 1) { const u32x2 pw = cur.pw[bj][n]; const f32x4 pp = (f32x4){bf_lo(pw.x), bf_hi(pw.x), bf_lo(pw.y), bf_hi(pw.y)}; v = sig4(I8 ? v : v * rs) * pp; }
;                         const f32x4 x = b + v; *(f32x4*)(out + o) = x;
;                         if (MODE == 0 && XB) { u32x2 w; w.x = cvt_pk_bf16(x[0], x[1]); w.y = cvt_pk_bf16(x[2], x[3]); *(u32x2*)(XB + o) = w; ss += (x[0] * x[0] + x[1] * x[1]) + (x[2] * x[2] + x[3] * x[3]);
;                             if (RM) mx = fmaxf(fmaxf(mx, fmaxf(fabsf(x[0]), fabsf(x[1]))), fmaxf(fabsf(x[2]), fabsf(x[3]))); } }
;                 if (MODE == 0 && XB) { ss += __shfl_xor(ss, 16); ss += __shfl_xor(ss, 32); if (fq == 0) unsafeAtomicAdd(SS + r, ss);
;                     if (RM) { mx = fmaxf(mx, __shfl_xor(mx, 16)); mx = fmaxf(mx, __shfl_xor(mx, 32)); if (fq == 0) atomicMax(RM + r, __builtin_bit_cast(unsigned, mx)); } }
	v_pk_add_f32 v[110:111], v[110:111], v[146:147]
	v_pk_add_f32 v[112:113], v[112:113], v[148:149]
	v_pk_add_f32 v[106:107], v[106:107], v[150:151]
	v_pk_add_f32 v[108:109], v[108:109], v[152:153]
	v_pk_add_f32 v[102:103], v[102:103], v[154:155]
	v_pk_add_f32 v[104:105], v[104:105], v[156:157]
	v_pk_add_f32 v[98:99], v[98:99], v[158:159]
	v_pk_add_f32 v[100:101], v[100:101], v[160:161]
	v_add_u32_e32 v162, 0x4000, v246
	global_load_dwordx4 v[146:149], v162, s[98:99] offset:0
	global_load_dwordx4 v[150:153], v162, s[98:99] offset:1024
	global_load_dwordx4 v[154:157], v162, s[98:99] offset:2048
	global_load_dwordx4 v[158:161], v162, s[98:99] offset:3072
	v_add_u32_e32 v163, 0x1000, v246
	v_add_u32_e32 v190, 0x20000, v250
	global_store_dwordx4 v163, v[110:113], s[98:99] offset:0
	v_cvt_pk_bf16_f32 v182, v110, v111
	v_cvt_pk_bf16_f32 v183, v112, v113
	v_mul_f32_e32 v166, v111, v111
	v_mul_f32_e32 v167, v113, v113
	global_store_dwordx2 v190, v[182:183], s[52:53] offset:0
	v_fmac_f32_e32 v166, v110, v110
	v_fmac_f32_e32 v167, v112, v112
	v_add_f32_e32 v164, v166, v167
	v_max3_f32 v165, |v110|, |v111|, 0
	v_max3_f32 v165, |v112|, |v113|, v165
	global_store_dwordx4 v163, v[106:109], s[98:99] offset:1024
	v_cvt_pk_bf16_f32 v184, v106, v107
	v_cvt_pk_bf16_f32 v185, v108, v109
	v_mul_f32_e32 v166, v107, v107
	v_mul_f32_e32 v167, v109, v109
	global_store_dwordx2 v190, v[184:185], s[52:53] offset:32
	v_fmac_f32_e32 v166, v106, v106
	v_fmac_f32_e32 v167, v108, v108
	v_add_f32_e32 v166, v166, v167
	v_add_f32_e32 v164, v164, v166
	v_max3_f32 v165, |v106|, |v107|, v165
	v_max3_f32 v165, |v108|, |v109|, v165
	global_store_dwordx4 v163, v[102:105], s[98:99] offset:2048
	v_cvt_pk_bf16_f32 v186, v102, v103
	v_cvt_pk_bf16_f32 v187, v104, v105
	v_mul_f32_e32 v166, v103, v103
	v_mul_f32_e32 v167, v105, v105
	global_store_dwordx2 v190, v[186:187], s[52:53] offset:256
	v_fmac_f32_e32 v166, v102, v102
	v_fmac_f32_e32 v167, v104, v104
	v_add_f32_e32 v166, v166, v167
	v_add_f32_e32 v164, v164, v166
	v_max3_f32 v165, |v102|, |v103|, v165
	v_max3_f32 v165, |v104|, |v105|, v165
	global_store_dwordx4 v163, v[98:101], s[98:99] offset:3072
	v_cvt_pk_bf16_f32 v188, v98, v99
	v_cvt_pk_bf16_f32 v189, v100, v101
	v_mul_f32_e32 v166, v99, v99
	v_mul_f32_e32 v167, v101, v101
	global_store_dwordx2 v190, v[188:189], s[52:53] offset:288
	v_fmac_f32_e32 v166, v98, v98
	v_fmac_f32_e32 v167, v100, v100
	v_add_f32_e32 v166, v166, v167
	v_add_f32_e32 v164, v164, v166
	v_max3_f32 v165, |v98|, |v99|, v165
	v_max3_f32 v165, |v100|, |v101|, v165
	ds_bpermute_b32 v168, v252, v164
	ds_bpermute_b32 v169, v252, v165
	s_waitcnt lgkmcnt(0)
	v_add_f32_e32 v164, v164, v168
	v_max_f32_e32 v165, v165, v169
	ds_bpermute_b32 v168, v253, v164
	ds_bpermute_b32 v169, v253, v165
	s_waitcnt lgkmcnt(0)
	v_add_f32_e32 v164, v164, v168
	v_max_f32_e32 v165, v165, v169
	s_mov_b64 exec, s[6:7]
	global_atomic_add_f32 v251, v164, s[10:11] offset:64
	global_atomic_umax v251, v165, s[12:13] offset:64
	s_mov_b64 exec, -1
	s_waitcnt vmcnt(28)
	v_pk_add_f32 v[94:95], v[94:95], v[196:197]
	v_pk_add_f32 v[96:97], v[96:97], v[198:199]
	v_pk_add_f32 v[90:91], v[90:91], v[200:201]
	v_pk_add_f32 v[92:93], v[92:93], v[202:203]
	v_pk_add_f32 v[86:87], v[86:87], v[204:205]
	v_pk_add_f32 v[88:89], v[88:89], v[206:207]
	v_pk_add_f32 v[82:83], v[82:83], v[208:209]
	v_pk_add_f32 v[84:85], v[84:85], v[210:211]
	v_add_u32_e32 v162, 0x5000, v246
	global_load_dwordx4 v[196:199], v162, s[98:99] offset:0
	global_load_dwordx4 v[200:203], v162, s[98:99] offset:1024
	global_load_dwordx4 v[204:207], v162, s[98:99] offset:2048
	global_load_dwordx4 v[208:211], v162, s[98:99] offset:3072
	v_add_u32_e32 v163, 0x2000, v246
	v_add_u32_e32 v190, 0x40000, v250
	global_store_dwordx4 v163, v[94:97], s[98:99] offset:0
	v_cvt_pk_bf16_f32 v182, v94, v95
	v_cvt_pk_bf16_f32 v183, v96, v97
	v_mul_f32_e32 v166, v95, v95
	v_mul_f32_e32 v167, v97, v97
	global_store_dwordx2 v190, v[182:183], s[52:53] offset:0
	v_fmac_f32_e32 v166, v94, v94
	v_fmac_f32_e32 v167, v96, v96
	v_add_f32_e32 v164, v166, v167
	v_max3_f32 v165, |v94|, |v95|, 0
	v_max3_f32 v165, |v96|, |v97|, v165
	global_store_dwordx4 v163, v[90:93], s[98:99] offset:1024
	v_cvt_pk_bf16_f32 v184, v90, v91
	v_cvt_pk_bf16_f32 v185, v92, v93
	v_mul_f32_e32 v166, v91, v91
	v_mul_f32_e32 v167, v93, v93
	global_store_dwordx2 v190, v[184:185], s[52:53] offset:32
	v_fmac_f32_e32 v166, v90, v90
	v_fmac_f32_e32 v167, v92, v92
	v_add_f32_e32 v166, v166, v167
	v_add_f32_e32 v164, v164, v166
	v_max3_f32 v165, |v90|, |v91|, v165
	v_max3_f32 v165, |v92|, |v93|, v165
	global_store_dwordx4 v163, v[86:89], s[98:99] offset:2048
	v_cvt_pk_bf16_f32 v186, v86, v87
	v_cvt_pk_bf16_f32 v187, v88, v89
	v_mul_f32_e32 v166, v87, v87
	v_mul_f32_e32 v167, v89, v89
	global_store_dwordx2 v190, v[186:187], s[52:53] offset:256
	v_fmac_f32_e32 v166, v86, v86
	v_fmac_f32_e32 v167, v88, v88
	v_add_f32_e32 v166, v166, v167
	v_add_f32_e32 v164, v164, v166
	v_max3_f32 v165, |v86|, |v87|, v165
	v_max3_f32 v165, |v88|, |v89|, v165
	global_store_dwordx4 v163, v[82:85], s[98:99] offset:3072
	v_cvt_pk_bf16_f32 v188, v82, v83
	v_cvt_pk_bf16_f32 v189, v84, v85
	v_mul_f32_e32 v166, v83, v83
	v_mul_f32_e32 v167, v85, v85
	global_store_dwordx2 v190, v[188:189], s[52:53] offset:288
	v_fmac_f32_e32 v166, v82, v82
	v_fmac_f32_e32 v167, v84, v84
	v_add_f32_e32 v166, v166, v167
	v_add_f32_e32 v164, v164, v166
	v_max3_f32 v165, |v82|, |v83|, v165
	v_max3_f32 v165, |v84|, |v85|, v165
	ds_bpermute_b32 v168, v252, v164
	ds_bpermute_b32 v169, v252, v165
	s_waitcnt lgkmcnt(0)
	v_add_f32_e32 v164, v164, v168
	v_max_f32_e32 v165, v165, v169
	ds_bpermute_b32 v168, v253, v164
	ds_bpermute_b32 v169, v253, v165
	s_waitcnt lgkmcnt(0)
; __device__ __forceinline__ unsigned cvt_pk_bf16(float lo, float hi) { unsigned r; asm volatile("s_nop 0\n\tv_cvt_pk_bf16_f32 %0, %1, %2" : "=v"(r) : "v"(lo), "v"(hi)); return r; }
; __device__ __forceinline__ f32x4 sig4(const f32x4 v) { return (f32x4){sigmoidf_(v[0]), sigmoidf_(v[1]), sigmoidf_(v[2]), sigmoidf_(v[3])}; }
;     __device__ __forceinline__ void operator()(const typename AccT<I8>::type (&acc)[2][2][4][2], const Unit& u, int wr, int wc, int fr, int fq) const {
;     ...
;         for (int s = 0; s < 8; ++s) { const int ai = s >> 2, m = s & 3; const int r = row0 + ai * HALF + m * 16; const size_t off = (size_t)r * 4096 + col0;
;                 if (s + 1 < 8) load_row(nxt, (size_t)(row0 + ((s + 1) >> 2) * HALF + ((s + 1) & 3) * 16) * 4096 + col0);
;                 const float rs = rsv[s];
;                 float ss = 0.f, mx = 0.f;
; #pragma unroll
;                 for (int bj = 0; bj < 2; ++bj)
; #pragma unroll
;                     for (int n = 0; n < 2; ++n) { const size_t o = off + bj * HALF + n * 16; const f32x4 b = cur.b[bj][n]; f32x4 v;
;                         if constexpr (I8) v = __builtin_convertvector(acc[ai][bj][m][n], f32x4) * rs * sv[bj][n]; else v = acc[ai][bj][m][n];
;                         if (MODE == 1) { const u32x2 pw = cur.pw[bj][n]; const f32x4 pp = (f32x4){bf_lo(pw.x), bf_hi(pw.x), bf_lo(pw.y), bf_hi(pw.y)}; v = sig4(I8 ? v : v * rs) * pp; }
;                         const f32x4 x = b + v; *(f32x4*)(out + o) = x;
;                         if (MODE == 0 && XB) { u32x2 w; w.x = cvt_pk_bf16(x[0], x[1]); w.y = cvt_pk_bf16(x[2], x[3]); *(u32x2*)(XB + o) = w; ss += (x[0] * x[0] + x[1] * x[1]) + (x[2] * x[2] + x[3] * x[3]);
;                             if (RM) mx = fmaxf(fmaxf(mx, fmaxf(fabsf(x[0]), fabsf(x[1]))), fmaxf(fabsf(x[2]), fabsf(x[3]))); } }
;                 if (MODE == 0 && XB) { ss += __shfl_xor(ss, 16); ss += __shfl_xor(ss, 32); if (fq == 0) unsafeAtomicAdd(SS + r, ss);
;                     if (RM) { mx = fmaxf(mx, __shfl_xor(mx, 16)); mx = fmaxf(mx, __shfl_xor(mx, 32)); if (fq == 0) atomicMax(RM + r, __builtin_bit_cast(unsigned, mx)); } }
	v_add_f32_e32 v164, v164, v168
	v_max_f32_e32 v165, v165, v169
	s_mov_b64 exec, s[6:7]
	global_atomic_add_f32 v251, v164, s[10:11] offset:128
	global_atomic_umax v251, v165, s[12:13] offset:128
	s_mov_b64 exec, -1
	s_waitcnt vmcnt(38)
	v_pk_add_f32 v[78:79], v[78:79], v[130:131]
	v_pk_add_f32 v[80:81], v[80:81], v[132:133]
	v_pk_add_f32 v[74:75], v[74:75], v[134:135]
	v_pk_add_f32 v[76:77], v[76:77], v[136:137]
	v_pk_add_f32 v[70:71], v[70:71], v[138:139]
	v_pk_add_f32 v[72:73], v[72:73], v[140:141]
	v_pk_add_f32 v[66:67], v[66:67], v[142:143]
	v_pk_add_f32 v[68:69], v[68:69], v[144:145]
	v_add_u32_e32 v162, 0x6000, v246
	global_load_dwordx4 v[130:133], v162, s[98:99] offset:0
	global_load_dwordx4 v[134:137], v162, s[98:99] offset:1024
	global_load_dwordx4 v[138:141], v162, s[98:99] offset:2048
	global_load_dwordx4 v[142:145], v162, s[98:99] offset:3072
	v_add_u32_e32 v163, 0x3000, v246
	v_add_u32_e32 v190, 0x60000, v250
	global_store_dwordx4 v163, v[78:81], s[98:99] offset:0
	v_cvt_pk_bf16_f32 v182, v78, v79
	v_cvt_pk_bf16_f32 v183, v80, v81
	v_mul_f32_e32 v166, v79, v79
	v_mul_f32_e32 v167, v81, v81
	global_store_dwordx2 v190, v[182:183], s[52:53] offset:0
	v_fmac_f32_e32 v166, v78, v78
	v_fmac_f32_e32 v167, v80, v80
	v_add_f32_e32 v164, v166, v167
	v_max3_f32 v165, |v78|, |v79|, 0
	v_max3_f32 v165, |v80|, |v81|, v165
	global_store_dwordx4 v163, v[74:77], s[98:99] offset:1024
	v_cvt_pk_bf16_f32 v184, v74, v75
	v_cvt_pk_bf16_f32 v185, v76, v77
	v_mul_f32_e32 v166, v75, v75
	v_mul_f32_e32 v167, v77, v77
	global_store_dwordx2 v190, v[184:185], s[52:53] offset:32
	v_fmac_f32_e32 v166, v74, v74
	v_fmac_f32_e32 v167, v76, v76
	v_add_f32_e32 v166, v166, v167
	v_add_f32_e32 v164, v164, v166
	v_max3_f32 v165, |v74|, |v75|, v165
	v_max3_f32 v165, |v76|, |v77|, v165
	global_store_dwordx4 v163, v[70:73], s[98:99] offset:2048
	v_cvt_pk_bf16_f32 v186, v70, v71
	v_cvt_pk_bf16_f32 v187, v72, v73
	v_mul_f32_e32 v166, v71, v71
	v_mul_f32_e32 v167, v73, v73
	global_store_dwordx2 v190, v[186:187], s[52:53] offset:256
	v_fmac_f32_e32 v166, v70, v70
	v_fmac_f32_e32 v167, v72, v72
	v_add_f32_e32 v166, v166, v167
	v_add_f32_e32 v164, v164, v166
	v_max3_f32 v165, |v70|, |v71|, v165
	v_max3_f32 v165, |v72|, |v73|, v165
	global_store_dwordx4 v163, v[66:69], s[98:99] offset:3072
	v_cvt_pk_bf16_f32 v188, v66, v67
	v_cvt_pk_bf16_f32 v189, v68, v69
	v_mul_f32_e32 v166, v67, v67
	v_mul_f32_e32 v167, v69, v69
	global_store_dwordx2 v190, v[188:189], s[52:53] offset:288
	v_fmac_f32_e32 v166, v66, v66
	v_fmac_f32_e32 v167, v68, v68
	v_add_f32_e32 v166, v166, v167
	v_add_f32_e32 v164, v164, v166
	v_max3_f32 v165, |v66|, |v67|, v165
	v_max3_f32 v165, |v68|, |v69|, v165
	ds_bpermute_b32 v168, v252, v164
	ds_bpermute_b32 v169, v252, v165
	s_waitcnt lgkmcnt(0)
	v_add_f32_e32 v164, v164, v168
	v_max_f32_e32 v165, v165, v169
	ds_bpermute_b32 v168, v253, v164
	ds_bpermute_b32 v169, v253, v165
	s_waitcnt lgkmcnt(0)
	v_add_f32_e32 v164, v164, v168
	v_max_f32_e32 v165, v165, v169
	s_mov_b64 exec, s[6:7]
	global_atomic_add_f32 v251, v164, s[10:11] offset:192
	global_atomic_umax v251, v165, s[12:13] offset:192
	s_mov_b64 exec, -1
	s_waitcnt vmcnt(38)
	v_pk_add_f32 v[62:63], v[62:63], v[146:147]
	v_pk_add_f32 v[64:65], v[64:65], v[148:149]
	v_pk_add_f32 v[58:59], v[58:59], v[150:151]
	v_pk_add_f32 v[60:61], v[60:61], v[152:153]
	v_pk_add_f32 v[54:55], v[54:55], v[154:155]
	v_pk_add_f32 v[56:57], v[56:57], v[156:157]
	v_pk_add_f32 v[50:51], v[50:51], v[158:159]
	v_pk_add_f32 v[52:53], v[52:53], v[160:161]
	v_add_u32_e32 v162, 0x7000, v246
	global_load_dwordx4 v[146:149], v162, s[98:99] offset:0
	global_load_dwordx4 v[150:153], v162, s[98:99] offset:1024
	global_load_dwordx4 v[154:157], v162, s[98:99] offset:2048
	global_load_dwordx4 v[158:161], v162, s[98:99] offset:3072
	v_add_u32_e32 v163, 0x4000, v246
	v_add_u32_e32 v190, 0x100000, v250
	global_store_dwordx4 v163, v[62:65], s[98:99] offset:0
	v_cvt_pk_bf16_f32 v182, v62, v63
	v_cvt_pk_bf16_f32 v183, v64, v65
	v_mul_f32_e32 v166, v63, v63
	v_mul_f32_e32 v167, v65, v65
	global_store_dwordx2 v190, v[182:183], s[52:53] offset:0
	v_fmac_f32_e32 v166, v62, v62
	v_fmac_f32_e32 v167, v64, v64
	v_add_f32_e32 v164, v166, v167
	v_max3_f32 v165, |v62|, |v63|, 0
	v_max3_f32 v165, |v64|, |v65|, v165
	global_store_dwordx4 v163, v[58:61], s[98:99] offset:1024
	v_cvt_pk_bf16_f32 v184, v58, v59
	v_cvt_pk_bf16_f32 v185, v60, v61
	v_mul_f32_e32 v166, v59, v59
	v_mul_f32_e32 v167, v61, v61
	global_store_dwordx2 v190, v[184:185], s[52:53] offset:32
	v_fmac_f32_e32 v166, v58, v58
	v_fmac_f32_e32 v167, v60, v60
	v_add_f32_e32 v166, v166, v167
	v_add_f32_e32 v164, v164, v166
	v_max3_f32 v165, |v58|, |v59|, v165
	v_max3_f32 v165, |v60|, |v61|, v165
	global_store_dwordx4 v163, v[54:57], s[98:99] offset:2048
	v_cvt_pk_bf16_f32 v186, v54, v55
	v_cvt_pk_bf16_f32 v187, v56, v57
	v_mul_f32_e32 v166, v55, v55
	v_mul_f32_e32 v167, v57, v57
	global_store_dwordx2 v190, v[186:187], s[52:53] offset:256
	v_fmac_f32_e32 v166, v54, v54
	v_fmac_f32_e32 v167, v56, v56
	v_add_f32_e32 v166, v166, v167
	v_add_f32_e32 v164, v164, v166
	v_max3_f32 v165, |v54|, |v55|, v165
	v_max3_f32 v165, |v56|, |v57|, v165
	global_store_dwordx4 v163, v[50:53], s[98:99] offset:3072
	v_cvt_pk_bf16_f32 v188, v50, v51
	v_cvt_pk_bf16_f32 v189, v52, v53
	v_mul_f32_e32 v166, v51, v51
	v_mul_f32_e32 v167, v53, v53
	global_store_dwordx2 v190, v[188:189], s[52:53] offset:288
	v_fmac_f32_e32 v166, v50, v50
	v_fmac_f32_e32 v167, v52, v52
	v_add_f32_e32 v166, v166, v167
	v_add_f32_e32 v164, v164, v166
	v_max3_f32 v165, |v50|, |v51|, v165
	v_max3_f32 v165, |v52|, |v53|, v165
	ds_bpermute_b32 v168, v252, v164
	ds_bpermute_b32 v169, v252, v165
	s_waitcnt lgkmcnt(0)
; __device__ __forceinline__ unsigned cvt_pk_bf16(float lo, float hi) { unsigned r; asm volatile("s_nop 0\n\tv_cvt_pk_bf16_f32 %0, %1, %2" : "=v"(r) : "v"(lo), "v"(hi)); return r; }
; __device__ __forceinline__ f32x4 sig4(const f32x4 v) { return (f32x4){sigmoidf_(v[0]), sigmoidf_(v[1]), sigmoidf_(v[2]), sigmoidf_(v[3])}; }
;     __device__ __forceinline__ void operator()(const typename AccT<I8>::type (&acc)[2][2][4][2], const Unit& u, int wr, int wc, int fr, int fq) const {
;     ...
;         for (int s = 0; s < 8; ++s) { const int ai = s >> 2, m = s & 3; const int r = row0 + ai * HALF + m * 16; const size_t off = (size_t)r * 4096 + col0;
;                 if (s + 1 < 8) load_row(nxt, (size_t)(row0 + ((s + 1) >> 2) * HALF + ((s + 1) & 3) * 16) * 4096 + col0);
;                 const float rs = rsv[s];
;                 float ss = 0.f, mx = 0.f;
; #pragma unroll
;                 for (int bj = 0; bj < 2; ++bj)
; #pragma unroll
;                     for (int n = 0; n < 2; ++n) { const size_t o = off + bj * HALF + n * 16; const f32x4 b = cur.b[bj][n]; f32x4 v;
;                         if constexpr (I8) v = __builtin_convertvector(acc[ai][bj][m][n], f32x4) * rs * sv[bj][n]; else v = acc[ai][bj][m][n];
;                         if (MODE == 1) { const u32x2 pw = cur.pw[bj][n]; const f32x4 pp = (f32x4){bf_lo(pw.x), bf_hi(pw.x), bf_lo(pw.y), bf_hi(pw.y)}; v = sig4(I8 ? v : v * rs) * pp; }
;                         const f32x4 x = b + v; *(f32x4*)(out + o) = x;
;                         if (MODE == 0 && XB) { u32x2 w; w.x = cvt_pk_bf16(x[0], x[1]); w.y = cvt_pk_bf16(x[2], x[3]); *(u32x2*)(XB + o) = w; ss += (x[0] * x[0] + x[1] * x[1]) + (x[2] * x[2] + x[3] * x[3]);
;                             if (RM) mx = fmaxf(fmaxf(mx, fmaxf(fabsf(x[0]), fabsf(x[1]))), fmaxf(fabsf(x[2]), fabsf(x[3]))); } }
;                 if (MODE == 0 && XB) { ss += __shfl_xor(ss, 16); ss += __shfl_xor(ss, 32); if (fq == 0) unsafeAtomicAdd(SS + r, ss);
;                     if (RM) { mx = fmaxf(mx, __shfl_xor(mx, 16)); mx = fmaxf(mx, __shfl_xor(mx, 32)); if (fq == 0) atomicMax(RM + r, __builtin_bit_cast(unsigned, mx)); } }
	v_add_f32_e32 v164, v164, v168
	v_max_f32_e32 v165, v165, v169
	ds_bpermute_b32 v168, v253, v164
	ds_bpermute_b32 v169, v253, v165
	s_waitcnt lgkmcnt(0)
	v_add_f32_e32 v164, v164, v168
	v_max_f32_e32 v165, v165, v169
	s_mov_b64 exec, s[6:7]
	global_atomic_add_f32 v251, v164, s[10:11] offset:512
	global_atomic_umax v251, v165, s[12:13] offset:512
	s_mov_b64 exec, -1
	s_waitcnt vmcnt(38)
	v_pk_add_f32 v[46:47], v[46:47], v[196:197]
	v_pk_add_f32 v[48:49], v[48:49], v[198:199]
	v_pk_add_f32 v[42:43], v[42:43], v[200:201]
	v_pk_add_f32 v[44:45], v[44:45], v[202:203]
	v_pk_add_f32 v[38:39], v[38:39], v[204:205]
	v_pk_add_f32 v[40:41], v[40:41], v[206:207]
	v_pk_add_f32 v[34:35], v[34:35], v[208:209]
	v_pk_add_f32 v[36:37], v[36:37], v[210:211]
	v_add_u32_e32 v163, 0x5000, v246
	v_add_u32_e32 v190, 0x120000, v250
	global_store_dwordx4 v163, v[46:49], s[98:99] offset:0
	v_cvt_pk_bf16_f32 v182, v46, v47
	v_cvt_pk_bf16_f32 v183, v48, v49
	v_mul_f32_e32 v166, v47, v47
	v_mul_f32_e32 v167, v49, v49
	global_store_dwordx2 v190, v[182:183], s[52:53] offset:0
	v_fmac_f32_e32 v166, v46, v46
	v_fmac_f32_e32 v167, v48, v48
	v_add_f32_e32 v164, v166, v167
	v_max3_f32 v165, |v46|, |v47|, 0
	v_max3_f32 v165, |v48|, |v49|, v165
	global_store_dwordx4 v163, v[42:45], s[98:99] offset:1024
	v_cvt_pk_bf16_f32 v184, v42, v43
	v_cvt_pk_bf16_f32 v185, v44, v45
	v_mul_f32_e32 v166, v43, v43
	v_mul_f32_e32 v167, v45, v45
	global_store_dwordx2 v190, v[184:185], s[52:53] offset:32
	v_fmac_f32_e32 v166, v42, v42
	v_fmac_f32_e32 v167, v44, v44
	v_add_f32_e32 v166, v166, v167
	v_add_f32_e32 v164, v164, v166
	v_max3_f32 v165, |v42|, |v43|, v165
	v_max3_f32 v165, |v44|, |v45|, v165
	global_store_dwordx4 v163, v[38:41], s[98:99] offset:2048
	v_cvt_pk_bf16_f32 v186, v38, v39
	v_cvt_pk_bf16_f32 v187, v40, v41
	v_mul_f32_e32 v166, v39, v39
	v_mul_f32_e32 v167, v41, v41
	global_store_dwordx2 v190, v[186:187], s[52:53] offset:256
	v_fmac_f32_e32 v166, v38, v38
	v_fmac_f32_e32 v167, v40, v40
	v_add_f32_e32 v166, v166, v167
	v_add_f32_e32 v164, v164, v166
	v_max3_f32 v165, |v38|, |v39|, v165
	v_max3_f32 v165, |v40|, |v41|, v165
	global_store_dwordx4 v163, v[34:37], s[98:99] offset:3072
	v_cvt_pk_bf16_f32 v188, v34, v35
	v_cvt_pk_bf16_f32 v189, v36, v37
	v_mul_f32_e32 v166, v35, v35
	v_mul_f32_e32 v167, v37, v37
	global_store_dwordx2 v190, v[188:189], s[52:53] offset:288
	v_fmac_f32_e32 v166, v34, v34
	v_fmac_f32_e32 v167, v36, v36
	v_add_f32_e32 v166, v166, v167
	v_add_f32_e32 v164, v164, v166
	v_max3_f32 v165, |v34|, |v35|, v165
	v_max3_f32 v165, |v36|, |v37|, v165
	ds_bpermute_b32 v168, v252, v164
	ds_bpermute_b32 v169, v252, v165
	s_waitcnt lgkmcnt(0)
	v_add_f32_e32 v164, v164, v168
	v_max_f32_e32 v165, v165, v169
	ds_bpermute_b32 v168, v253, v164
	ds_bpermute_b32 v169, v253, v165
	s_waitcnt lgkmcnt(0)
	v_add_f32_e32 v164, v164, v168
	v_max_f32_e32 v165, v165, v169
	s_mov_b64 exec, s[6:7]
	global_atomic_add_f32 v251, v164, s[10:11] offset:576
	global_atomic_umax v251, v165, s[12:13] offset:576
	s_mov_b64 exec, -1
	s_waitcnt vmcnt(34)
	v_pk_add_f32 v[30:31], v[30:31], v[130:131]
	v_pk_add_f32 v[32:33], v[32:33], v[132:133]
	v_pk_add_f32 v[26:27], v[26:27], v[134:135]
	v_pk_add_f32 v[28:29], v[28:29], v[136:137]
	v_pk_add_f32 v[18:19], v[18:19], v[138:139]
	v_pk_add_f32 v[20:21], v[20:21], v[140:141]
	v_pk_add_f32 v[14:15], v[14:15], v[142:143]
	v_pk_add_f32 v[16:17], v[16:17], v[144:145]
	v_add_u32_e32 v163, 0x6000, v246
	v_add_u32_e32 v190, 0x140000, v250
	global_store_dwordx4 v163, v[30:33], s[98:99] offset:0
	v_cvt_pk_bf16_f32 v182, v30, v31
	v_cvt_pk_bf16_f32 v183, v32, v33
	v_mul_f32_e32 v166, v31, v31
	v_mul_f32_e32 v167, v33, v33
	global_store_dwordx2 v190, v[182:183], s[52:53] offset:0
	v_fmac_f32_e32 v166, v30, v30
	v_fmac_f32_e32 v167, v32, v32
	v_add_f32_e32 v164, v166, v167
	v_max3_f32 v165, |v30|, |v31|, 0
	v_max3_f32 v165, |v32|, |v33|, v165
	global_store_dwordx4 v163, v[26:29], s[98:99] offset:1024
	v_cvt_pk_bf16_f32 v184, v26, v27
	v_cvt_pk_bf16_f32 v185, v28, v29
	v_mul_f32_e32 v166, v27, v27
	v_mul_f32_e32 v167, v29, v29
	global_store_dwordx2 v190, v[184:185], s[52:53] offset:32
	v_fmac_f32_e32 v166, v26, v26
	v_fmac_f32_e32 v167, v28, v28
	v_add_f32_e32 v166, v166, v167
	v_add_f32_e32 v164, v164, v166
	v_max3_f32 v165, |v26|, |v27|, v165
	v_max3_f32 v165, |v28|, |v29|, v165
	global_store_dwordx4 v163, v[18:21], s[98:99] offset:2048
	v_cvt_pk_bf16_f32 v186, v18, v19
	v_cvt_pk_bf16_f32 v187, v20, v21
	v_mul_f32_e32 v166, v19, v19
	v_mul_f32_e32 v167, v21, v21
	global_store_dwordx2 v190, v[186:187], s[52:53] offset:256
	v_fmac_f32_e32 v166, v18, v18
	v_fmac_f32_e32 v167, v20, v20
	v_add_f32_e32 v166, v166, v167
	v_add_f32_e32 v164, v164, v166
	v_max3_f32 v165, |v18|, |v19|, v165
	v_max3_f32 v165, |v20|, |v21|, v165
	global_store_dwordx4 v163, v[14:17], s[98:99] offset:3072
	v_cvt_pk_bf16_f32 v188, v14, v15
	v_cvt_pk_bf16_f32 v189, v16, v17
	v_mul_f32_e32 v166, v15, v15
	v_mul_f32_e32 v167, v17, v17
	global_store_dwordx2 v190, v[188:189], s[52:53] offset:288
	v_fmac_f32_e32 v166, v14, v14
	v_fmac_f32_e32 v167, v16, v16
	v_add_f32_e32 v166, v166, v167
	v_add_f32_e32 v164, v164, v166
	v_max3_f32 v165, |v14|, |v15|, v165
	v_max3_f32 v165, |v16|, |v17|, v165
	ds_bpermute_b32 v168, v252, v164
	ds_bpermute_b32 v169, v252, v165
	s_waitcnt lgkmcnt(0)
; __device__ __forceinline__ unsigned cvt_pk_bf16(float lo, float hi) { unsigned r; asm volatile("s_nop 0\n\tv_cvt_pk_bf16_f32 %0, %1, %2" : "=v"(r) : "v"(lo), "v"(hi)); return r; }
; __device__ __forceinline__ f32x4 sig4(const f32x4 v) { return (f32x4){sigmoidf_(v[0]), sigmoidf_(v[1]), sigmoidf_(v[2]), sigmoidf_(v[3])}; }
;     __device__ __forceinline__ void operator()(const typename AccT<I8>::type (&acc)[2][2][4][2], const Unit& u, int wr, int wc, int fr, int fq) const {
;     ...
;         for (int s = 0; s < 8; ++s) { const int ai = s >> 2, m = s & 3; const int r = row0 + ai * HALF + m * 16; const size_t off = (size_t)r * 4096 + col0;
;                 if (s + 1 < 8) load_row(nxt, (size_t)(row0 + ((s + 1) >> 2) * HALF + ((s + 1) & 3) * 16) * 4096 + col0);
;                 const float rs = rsv[s];
;                 float ss = 0.f, mx = 0.f;
; #pragma unroll
;                 for (int bj = 0; bj < 2; ++bj)
; #pragma unroll
;                     for (int n = 0; n < 2; ++n) { const size_t o = off + bj * HALF + n * 16; const f32x4 b = cur.b[bj][n]; f32x4 v;
;                         if constexpr (I8) v = __builtin_convertvector(acc[ai][bj][m][n], f32x4) * rs * sv[bj][n]; else v = acc[ai][bj][m][n];
;                         if (MODE == 1) { const u32x2 pw = cur.pw[bj][n]; const f32x4 pp = (f32x4){bf_lo(pw.x), bf_hi(pw.x), bf_lo(pw.y), bf_hi(pw.y)}; v = sig4(I8 ? v : v * rs) * pp; }
;                         const f32x4 x = b + v; *(f32x4*)(out + o) = x;
;                         if (MODE == 0 && XB) { u32x2 w; w.x = cvt_pk_bf16(x[0], x[1]); w.y = cvt_pk_bf16(x[2], x[3]); *(u32x2*)(XB + o) = w; ss += (x[0] * x[0] + x[1] * x[1]) + (x[2] * x[2] + x[3] * x[3]);
;                             if (RM) mx = fmaxf(fmaxf(mx, fmaxf(fabsf(x[0]), fabsf(x[1]))), fmaxf(fabsf(x[2]), fabsf(x[3]))); } }
;                 if (MODE == 0 && XB) { ss += __shfl_xor(ss, 16); ss += __shfl_xor(ss, 32); if (fq == 0) unsafeAtomicAdd(SS + r, ss);
;                     if (RM) { mx = fmaxf(mx, __shfl_xor(mx, 16)); mx = fmaxf(mx, __shfl_xor(mx, 32)); if (fq == 0) atomicMax(RM + r, __builtin_bit_cast(unsigned, mx)); } }
;                 cur = nxt; }
	v_add_f32_e32 v164, v164, v168
	v_max_f32_e32 v165, v165, v169
	ds_bpermute_b32 v168, v253, v164
	ds_bpermute_b32 v169, v253, v165
	s_waitcnt lgkmcnt(0)
	v_add_f32_e32 v164, v164, v168
	v_max_f32_e32 v165, v165, v169
	s_mov_b64 exec, s[6:7]
	global_atomic_add_f32 v251, v164, s[10:11] offset:640
	global_atomic_umax v251, v165, s[12:13] offset:640
	s_mov_b64 exec, -1
	s_waitcnt vmcnt(30)
	v_pk_add_f32 v[22:23], v[22:23], v[146:147]
	v_pk_add_f32 v[24:25], v[24:25], v[148:149]
	v_pk_add_f32 v[10:11], v[10:11], v[150:151]
	v_pk_add_f32 v[12:13], v[12:13], v[152:153]
	v_pk_add_f32 v[6:7], v[6:7], v[154:155]
	v_pk_add_f32 v[8:9], v[8:9], v[156:157]
	v_pk_add_f32 v[2:3], v[2:3], v[158:159]
	v_pk_add_f32 v[4:5], v[4:5], v[160:161]
	v_add_u32_e32 v163, 0x7000, v246
	v_add_u32_e32 v190, 0x160000, v250
	global_store_dwordx4 v163, v[22:25], s[98:99] offset:0
	v_cvt_pk_bf16_f32 v182, v22, v23
	v_cvt_pk_bf16_f32 v183, v24, v25
	v_mul_f32_e32 v166, v23, v23
	v_mul_f32_e32 v167, v25, v25
	global_store_dwordx2 v190, v[182:183], s[52:53] offset:0
	v_fmac_f32_e32 v166, v22, v22
	v_fmac_f32_e32 v167, v24, v24
	v_add_f32_e32 v164, v166, v167
	v_max3_f32 v165, |v22|, |v23|, 0
	v_max3_f32 v165, |v24|, |v25|, v165
	global_store_dwordx4 v163, v[10:13], s[98:99] offset:1024
	v_cvt_pk_bf16_f32 v184, v10, v11
	v_cvt_pk_bf16_f32 v185, v12, v13
	v_mul_f32_e32 v166, v11, v11
	v_mul_f32_e32 v167, v13, v13
	global_store_dwordx2 v190, v[184:185], s[52:53] offset:32
	v_fmac_f32_e32 v166, v10, v10
	v_fmac_f32_e32 v167, v12, v12
	v_add_f32_e32 v166, v166, v167
	v_add_f32_e32 v164, v164, v166
	v_max3_f32 v165, |v10|, |v11|, v165
	v_max3_f32 v165, |v12|, |v13|, v165
	global_store_dwordx4 v163, v[6:9], s[98:99] offset:2048
	v_cvt_pk_bf16_f32 v186, v6, v7
	v_cvt_pk_bf16_f32 v187, v8, v9
	v_mul_f32_e32 v166, v7, v7
	v_mul_f32_e32 v167, v9, v9
	global_store_dwordx2 v190, v[186:187], s[52:53] offset:256
	v_fmac_f32_e32 v166, v6, v6
	v_fmac_f32_e32 v167, v8, v8
	v_add_f32_e32 v166, v166, v167
	v_add_f32_e32 v164, v164, v166
	v_max3_f32 v165, |v6|, |v7|, v165
	v_max3_f32 v165, |v8|, |v9|, v165
	global_store_dwordx4 v163, v[2:5], s[98:99] offset:3072
	v_cvt_pk_bf16_f32 v188, v2, v3
	v_cvt_pk_bf16_f32 v189, v4, v5
	v_mul_f32_e32 v166, v3, v3
	v_mul_f32_e32 v167, v5, v5
	global_store_dwordx2 v190, v[188:189], s[52:53] offset:288
	v_fmac_f32_e32 v166, v2, v2
	v_fmac_f32_e32 v167, v4, v4
	v_add_f32_e32 v166, v166, v167
	v_add_f32_e32 v164, v164, v166
	v_max3_f32 v165, |v2|, |v3|, v165
	v_max3_f32 v165, |v4|, |v5|, v165
	ds_bpermute_b32 v168, v252, v164
	ds_bpermute_b32 v169, v252, v165
	s_waitcnt lgkmcnt(0)
	v_add_f32_e32 v164, v164, v168
	v_max_f32_e32 v165, v165, v169
	ds_bpermute_b32 v168, v253, v164
	ds_bpermute_b32 v169, v253, v165
	s_waitcnt lgkmcnt(0)
	v_add_f32_e32 v164, v164, v168
	v_max_f32_e32 v165, v165, v169
	s_mov_b64 exec, s[6:7]
	global_atomic_add_f32 v251, v164, s[10:11] offset:704
	global_atomic_umax v251, v165, s[12:13] offset:704
	s_mov_b64 exec, -1
.LBB0_2151:
	s_andn2_b64 vcc, exec, s[4:5]
	s_mov_b64 s[2:3], -1
	s_cbranch_vccnz .LBB0_2084
	s_andn2_b64 vcc, exec, s[0:1]
	s_cbranch_vccnz .LBB0_2083
	s_barrier
	s_branch .LBB0_2083
.LBB0_2162:
	s_waitcnt vmcnt(0)
	s_barrier
	s_cmp_lt_i32 s73, 14
	s_cbranch_scc1 .LBB0_2220
	s_branch .LBB0_2167
